# P3: GB gate words loaded once in the half-0 epilogue and kept in v218-v249 across the second K half (final epilogue no longer reloads them), on cvb
# baseline (speedup 1.0000x reference)
; __device__ __forceinline__ u32x4 pack8_bf16(const float (&o)[8]) { u32x4 w; w.x = cvt_pk_bf16(o[0], o[1]); w.y = cvt_pk_bf16(o[2], o[3]); w.z = cvt_pk_bf16(o[4], o[5]); w.w = cvt_pk_bf16(o[6], o[7]); return w; }
;     __device__ __forceinline__ void operator()(f32x4 (&acc)[2][2][4][2], const Unit& u, int wr, int wc, int fr, int fq) const {
;     ...
;         const int row0 = u.pm * BM + wr * 64 + fr;
;         u32x2 gbv[2][4][2];
; #pragma unroll
;         for (int ai = 0; ai < 2; ++ai)
; #pragma unroll
;             for (int m = 0; m < 4; ++m)
; #pragma unroll
;                 for (int bj = 0; bj < 2; ++bj) gbv[ai][m][bj] = *(const u32x2*)(GB + (size_t)(row0 + ai * HALF + m * 16) * 1024 + u.pn * BM + bj * HALF + wc * 32 + 8 * fq);
; #pragma unroll
;         for (int ai = 0; ai < 2; ++ai)
; #pragma unroll
;             for (int m = 0; m < 4; ++m)
; #pragma unroll
;                 for (int bj = 0; bj < 2; ++bj) {
;                     const size_t off = (size_t)(row0 + ai * HALF + m * 16) * 1024 + u.pn * BM + bj * HALF + wc * 32 + 8 * fq;
;                     const u32x2 b = gbv[ai][m][bj]; float o[8];
; #pragma unroll
;                     for (int k = 0; k < 8; ++k) { const float qb = (float)((b[k >> 2] >> (8 * (k & 3))) & 255u); o[k] = acc[ai][bj][m][k >> 2][k & 3] * (qb * (1.0f / 255.0f)); }
;                     *(u32x4*)(MIXED + off) = pack8_bf16(o);
.LBB0_798:
	s_cmp_lg_u32 s49, 0
	v_lshl_add_u32 v150, s48, 8, v139
	s_cselect_b64 s[46:47], -1, 0
	v_or_b32_e32 v156, 16, v150
	v_or_b32_e32 v154, 32, v150
	v_or_b32_e32 v152, 48, v150
	s_and_b64 vcc, exec, s[46:47]
	v_ashrrev_i32_e32 v151, 31, v150
	v_ashrrev_i32_e32 v157, 31, v156
	v_ashrrev_i32_e32 v155, 31, v154
	v_ashrrev_i32_e32 v153, 31, v152
	s_cbranch_vccz .LBB0_806
	s_lshl_b32 s48, s77, 8
	s_ashr_i32 s49, s48, 31
	v_lshl_add_u64 v[160:161], v[140:141], 0, s[48:49]
	v_lshlrev_b64 v[158:159], 10, v[150:151]
	v_lshl_add_u64 v[158:159], v[160:161], 0, v[158:159]
	v_mov_b32_e32 v190, v218
	v_mov_b32_e32 v191, v219
	v_mov_b32_e32 v192, v220
	v_mov_b32_e32 v193, v221
	v_lshlrev_b64 v[158:159], 10, v[156:157]
	v_lshl_add_u64 v[168:169], v[160:161], 0, v[158:159]
	v_mov_b32_e32 v198, v222
	v_mov_b32_e32 v199, v223
	v_add_u32_e32 v176, 0x80, v150
	v_add_u32_e32 v170, 0x90, v150
	v_add_u32_e32 v164, 0xa0, v150
	v_add_u32_e32 v158, 0xb0, v150
	v_ashrrev_i32_e32 v177, 31, v176
	v_ashrrev_i32_e32 v171, 31, v170
	v_ashrrev_i32_e32 v165, 31, v164
	v_ashrrev_i32_e32 v159, 31, v158
	v_lshlrev_b64 v[162:163], 10, v[154:155]
	v_lshlrev_b64 v[166:167], 10, v[152:153]
	v_lshlrev_b64 v[172:173], 11, v[150:151]
	v_lshlrev_b64 v[174:175], 10, v[176:177]
	v_lshlrev_b64 v[178:179], 10, v[170:171]
	v_lshlrev_b64 v[180:181], 10, v[164:165]
	v_lshlrev_b64 v[182:183], 10, v[158:159]
	v_lshl_add_u64 v[172:173], s[12:13], 0, v[172:173]
	s_lshl_b64 s[48:49], s[48:49], 1
	v_lshl_add_u64 v[162:163], v[160:161], 0, v[162:163]
	v_lshl_add_u64 v[166:167], v[160:161], 0, v[166:167]
	v_lshl_add_u64 v[174:175], v[160:161], 0, v[174:175]
	v_lshl_add_u64 v[194:195], v[160:161], 0, v[178:179]
	v_lshl_add_u64 v[196:197], v[160:161], 0, v[180:181]
	v_lshl_add_u64 v[160:161], v[160:161], 0, v[182:183]
	v_lshl_add_u64 v[200:201], v[172:173], 0, s[48:49]
	v_mov_b32_e32 v202, v224
	v_mov_b32_e32 v203, v225
	v_mov_b32_e32 v204, v226
	v_mov_b32_e32 v205, v227
	v_mov_b32_e32 v206, v228
	v_mov_b32_e32 v207, v229
	v_mov_b32_e32 v184, v230
	v_mov_b32_e32 v185, v231
	v_mov_b32_e32 v182, v232
	v_mov_b32_e32 v183, v233
	v_mov_b32_e32 v180, v234
	v_mov_b32_e32 v181, v235
	v_mov_b32_e32 v178, v236
	v_mov_b32_e32 v179, v237
	s_nop 0
	v_mov_b32_e32 v174, v238
	v_mov_b32_e32 v175, v239
	v_mov_b32_e32 v172, v240
	v_mov_b32_e32 v173, v241
	v_mov_b32_e32 v168, v242
	v_mov_b32_e32 v169, v243
	v_mov_b32_e32 v166, v244
	v_mov_b32_e32 v167, v245
	v_mov_b32_e32 v162, v246
	v_mov_b32_e32 v163, v247
	s_nop 0
	v_mov_b32_e32 v160, v248
	v_mov_b32_e32 v161, v249
	v_lshl_add_u64 v[194:195], v[200:201], 0, s[4:5]
	v_lshl_add_u64 v[200:201], v[194:195], 0, v[136:137]
	v_lshlrev_b64 v[176:177], 11, v[176:177]
	v_lshl_add_u64 v[176:177], s[12:13], 0, v[176:177]
	v_lshl_add_u64 v[176:177], v[176:177], 0, s[48:49]
	v_lshl_add_u64 v[176:177], v[176:177], 0, s[4:5]
	v_lshlrev_b64 v[170:171], 11, v[170:171]
	v_lshl_add_u64 v[170:171], s[12:13], 0, v[170:171]
	v_lshl_add_u64 v[170:171], v[170:171], 0, s[48:49]
	v_lshl_add_u64 v[170:171], v[170:171], 0, s[4:5]
	v_lshlrev_b64 v[164:165], 11, v[164:165]
	v_lshl_add_u64 v[164:165], s[12:13], 0, v[164:165]
	v_lshl_add_u64 v[164:165], v[164:165], 0, s[48:49]
	v_lshl_add_u64 v[164:165], v[164:165], 0, s[4:5]
	v_lshlrev_b64 v[158:159], 11, v[158:159]
	v_lshl_add_u64 v[158:159], s[12:13], 0, v[158:159]
	v_lshl_add_u64 v[158:159], v[158:159], 0, s[48:49]
	v_lshl_add_u64 v[158:159], v[158:159], 0, s[4:5]
	s_waitcnt vmcnt(0)
	v_cvt_f32_ubyte1_e32 v195, v190
	v_cvt_f32_ubyte0_e32 v194, v190
	v_cvt_f32_ubyte3_e32 v197, v190
	v_cvt_f32_ubyte2_e32 v196, v190
	v_cvt_f32_ubyte1_e32 v209, v191
	v_cvt_f32_ubyte0_e32 v208, v191
	v_cvt_f32_ubyte3_e32 v211, v191
	v_cvt_f32_ubyte2_e32 v210, v191
	v_cvt_f32_ubyte1_e32 v191, v192
	v_cvt_f32_ubyte0_e32 v190, v192
	v_cvt_f32_ubyte3_e32 v213, v192
	v_cvt_f32_ubyte2_e32 v212, v192
	v_cvt_f32_ubyte1_e32 v215, v193
	v_cvt_f32_ubyte0_e32 v214, v193
	v_cvt_f32_ubyte3_e32 v217, v193
	v_cvt_f32_ubyte2_e32 v216, v193
	v_pk_mul_f32 v[192:193], v[194:195], s[18:19] op_sel_hi:[1,0]
	v_pk_mul_f32 v[194:195], v[196:197], s[18:19] op_sel_hi:[1,0]
	v_pk_mul_f32 v[196:197], v[208:209], s[18:19] op_sel_hi:[1,0]
	v_pk_mul_f32 v[208:209], v[210:211], s[18:19] op_sel_hi:[1,0]
	v_pk_mul_f32 v[190:191], v[190:191], s[18:19] op_sel_hi:[1,0]
	v_pk_mul_f32 v[210:211], v[212:213], s[18:19] op_sel_hi:[1,0]
	v_pk_mul_f32 v[212:213], v[214:215], s[18:19] op_sel_hi:[1,0]
	v_pk_mul_f32 v[214:215], v[216:217], s[18:19] op_sel_hi:[1,0]
	v_pk_mul_f32 v[192:193], v[124:125], v[192:193]
	v_pk_mul_f32 v[194:195], v[126:127], v[194:195]
	v_pk_mul_f32 v[196:197], v[120:121], v[196:197]
	v_pk_mul_f32 v[216:217], v[92:93], v[190:191]
	v_pk_mul_f32 v[210:211], v[94:95], v[210:211]
	v_pk_mul_f32 v[212:213], v[88:89], v[212:213]
	v_pk_mul_f32 v[214:215], v[90:91], v[214:215]
	v_pk_mul_f32 v[208:209], v[122:123], v[208:209]
	v_cvt_pk_bf16_f32 v190, v192, v193
	v_cvt_pk_bf16_f32 v191, v194, v195
	v_cvt_pk_bf16_f32 v192, v196, v197
	v_cvt_pk_bf16_f32 v194, v216, v217
	v_cvt_pk_bf16_f32 v195, v210, v211
	v_cvt_pk_bf16_f32 v196, v212, v213
	v_cvt_pk_bf16_f32 v197, v214, v215
	v_cvt_pk_bf16_f32 v193, v208, v209
	global_store_dwordx4 v[200:201], v[194:197], off offset:256
	global_store_dwordx4 v[200:201], v[190:193], off
	v_cvt_f32_ubyte3_e32 v201, v199
	v_lshlrev_b64 v[194:195], 11, v[156:157]
	v_cvt_f32_ubyte1_e32 v191, v198
	v_cvt_f32_ubyte0_e32 v190, v198
	v_cvt_f32_ubyte3_e32 v193, v198
	v_cvt_f32_ubyte2_e32 v192, v198
	v_cvt_f32_ubyte1_e32 v197, v199
	v_cvt_f32_ubyte0_e32 v196, v199
	v_cvt_f32_ubyte2_e32 v200, v199
	v_lshl_add_u64 v[194:195], s[12:13], 0, v[194:195]
; __device__ __forceinline__ u32x4 pack8_bf16(const float (&o)[8]) { u32x4 w; w.x = cvt_pk_bf16(o[0], o[1]); w.y = cvt_pk_bf16(o[2], o[3]); w.z = cvt_pk_bf16(o[4], o[5]); w.w = cvt_pk_bf16(o[6], o[7]); return w; }
;     __device__ __forceinline__ void operator()(f32x4 (&acc)[2][2][4][2], const Unit& u, int wr, int wc, int fr, int fq) const {
;     ...
;                 for (int bj = 0; bj < 2; ++bj) {
;                     const size_t off = (size_t)(row0 + ai * HALF + m * 16) * 1024 + u.pn * BM + bj * HALF + wc * 32 + 8 * fq;
;                     const u32x2 b = gbv[ai][m][bj]; float o[8];
; #pragma unroll
;                     for (int k = 0; k < 8; ++k) { const float qb = (float)((b[k >> 2] >> (8 * (k & 3))) & 255u); o[k] = acc[ai][bj][m][k >> 2][k & 3] * (qb * (1.0f / 255.0f)); }
;                     *(u32x4*)(MIXED + off) = pack8_bf16(o);
	v_pk_mul_f32 v[190:191], v[190:191], s[18:19] op_sel_hi:[1,0]
	v_pk_mul_f32 v[192:193], v[192:193], s[18:19] op_sel_hi:[1,0]
	v_pk_mul_f32 v[196:197], v[196:197], s[18:19] op_sel_hi:[1,0]
	v_pk_mul_f32 v[198:199], v[200:201], s[18:19] op_sel_hi:[1,0]
	v_lshl_add_u64 v[194:195], v[194:195], 0, s[48:49]
	v_pk_mul_f32 v[190:191], v[116:117], v[190:191]
	v_pk_mul_f32 v[192:193], v[118:119], v[192:193]
	v_pk_mul_f32 v[196:197], v[112:113], v[196:197]
	v_pk_mul_f32 v[198:199], v[114:115], v[198:199]
	v_lshl_add_u64 v[194:195], v[194:195], 0, s[4:5]
	v_cvt_pk_bf16_f32 v190, v190, v191
	v_cvt_pk_bf16_f32 v191, v192, v193
	v_cvt_pk_bf16_f32 v192, v196, v197
	v_cvt_pk_bf16_f32 v193, v198, v199
	v_lshl_add_u64 v[194:195], v[194:195], 0, v[136:137]
	global_store_dwordx4 v[194:195], v[190:193], off
	v_cvt_f32_ubyte1_e32 v197, v203
	v_cvt_f32_ubyte0_e32 v196, v203
	v_cvt_f32_ubyte1_e32 v191, v202
	v_cvt_f32_ubyte0_e32 v190, v202
	v_cvt_f32_ubyte3_e32 v193, v202
	v_cvt_f32_ubyte2_e32 v192, v202
	v_cvt_f32_ubyte3_e32 v199, v203
	v_cvt_f32_ubyte2_e32 v198, v203
	v_pk_mul_f32 v[190:191], v[190:191], s[18:19] op_sel_hi:[1,0]
	v_pk_mul_f32 v[192:193], v[192:193], s[18:19] op_sel_hi:[1,0]
	v_pk_mul_f32 v[196:197], v[196:197], s[18:19] op_sel_hi:[1,0]
	v_pk_mul_f32 v[198:199], v[198:199], s[18:19] op_sel_hi:[1,0]
	v_pk_mul_f32 v[190:191], v[84:85], v[190:191]
	v_pk_mul_f32 v[192:193], v[86:87], v[192:193]
	v_pk_mul_f32 v[196:197], v[80:81], v[196:197]
	v_pk_mul_f32 v[198:199], v[82:83], v[198:199]
	v_cvt_pk_bf16_f32 v190, v190, v191
	v_cvt_pk_bf16_f32 v191, v192, v193
	v_cvt_pk_bf16_f32 v192, v196, v197
	v_cvt_pk_bf16_f32 v193, v198, v199
	global_store_dwordx4 v[194:195], v[190:193], off offset:256
	v_lshlrev_b64 v[194:195], 11, v[154:155]
	v_cvt_f32_ubyte1_e32 v197, v205
	v_cvt_f32_ubyte1_e32 v191, v204
	v_cvt_f32_ubyte0_e32 v190, v204
	v_cvt_f32_ubyte3_e32 v193, v204
	v_cvt_f32_ubyte2_e32 v192, v204
	v_cvt_f32_ubyte0_e32 v196, v205
	v_cvt_f32_ubyte3_e32 v199, v205
	v_cvt_f32_ubyte2_e32 v198, v205
	v_lshl_add_u64 v[194:195], s[12:13], 0, v[194:195]
	v_pk_mul_f32 v[190:191], v[190:191], s[18:19] op_sel_hi:[1,0]
	v_pk_mul_f32 v[192:193], v[192:193], s[18:19] op_sel_hi:[1,0]
	v_pk_mul_f32 v[196:197], v[196:197], s[18:19] op_sel_hi:[1,0]
	v_pk_mul_f32 v[198:199], v[198:199], s[18:19] op_sel_hi:[1,0]
	v_lshl_add_u64 v[194:195], v[194:195], 0, s[48:49]
	v_pk_mul_f32 v[190:191], v[108:109], v[190:191]
	v_pk_mul_f32 v[192:193], v[110:111], v[192:193]
	v_pk_mul_f32 v[196:197], v[104:105], v[196:197]
	v_pk_mul_f32 v[198:199], v[106:107], v[198:199]
	v_lshl_add_u64 v[194:195], v[194:195], 0, s[4:5]
	v_cvt_pk_bf16_f32 v190, v190, v191
	v_cvt_pk_bf16_f32 v191, v192, v193
	v_cvt_pk_bf16_f32 v192, v196, v197
	v_cvt_pk_bf16_f32 v193, v198, v199
	v_lshl_add_u64 v[194:195], v[194:195], 0, v[136:137]
	global_store_dwordx4 v[194:195], v[190:193], off
	v_cvt_f32_ubyte1_e32 v197, v207
	v_cvt_f32_ubyte0_e32 v196, v207
	v_cvt_f32_ubyte1_e32 v191, v206
	v_cvt_f32_ubyte0_e32 v190, v206
	v_cvt_f32_ubyte3_e32 v193, v206
	v_cvt_f32_ubyte2_e32 v192, v206
	v_cvt_f32_ubyte3_e32 v199, v207
	v_cvt_f32_ubyte2_e32 v198, v207
	v_pk_mul_f32 v[190:191], v[190:191], s[18:19] op_sel_hi:[1,0]
	v_pk_mul_f32 v[192:193], v[192:193], s[18:19] op_sel_hi:[1,0]
	v_pk_mul_f32 v[196:197], v[196:197], s[18:19] op_sel_hi:[1,0]
	v_pk_mul_f32 v[198:199], v[198:199], s[18:19] op_sel_hi:[1,0]
	v_pk_mul_f32 v[190:191], v[76:77], v[190:191]
	v_pk_mul_f32 v[192:193], v[78:79], v[192:193]
	v_pk_mul_f32 v[196:197], v[72:73], v[196:197]
	v_pk_mul_f32 v[198:199], v[74:75], v[198:199]
	v_cvt_pk_bf16_f32 v190, v190, v191
	v_cvt_pk_bf16_f32 v191, v192, v193
	v_cvt_pk_bf16_f32 v192, v196, v197
	v_cvt_pk_bf16_f32 v193, v198, v199
	global_store_dwordx4 v[194:195], v[190:193], off offset:256
	v_cvt_f32_ubyte3_e32 v199, v185
	v_cvt_f32_ubyte2_e32 v198, v185
	v_cvt_f32_ubyte1_e32 v191, v184
	v_cvt_f32_ubyte0_e32 v190, v184
	v_cvt_f32_ubyte3_e32 v193, v184
	v_cvt_f32_ubyte2_e32 v192, v184
	v_pk_mul_f32 v[190:191], v[190:191], s[18:19] op_sel_hi:[1,0]
	v_pk_mul_f32 v[192:193], v[192:193], s[18:19] op_sel_hi:[1,0]
	v_cvt_f32_ubyte1_e32 v197, v185
	v_cvt_f32_ubyte0_e32 v196, v185
	v_pk_mul_f32 v[184:185], v[198:199], s[18:19] op_sel_hi:[1,0]
	v_lshlrev_b64 v[194:195], 11, v[152:153]
	v_pk_mul_f32 v[190:191], v[100:101], v[190:191]
	v_pk_mul_f32 v[192:193], v[102:103], v[192:193]
	v_pk_mul_f32 v[184:185], v[98:99], v[184:185]
	v_cvt_pk_bf16_f32 v190, v190, v191
	v_cvt_pk_bf16_f32 v191, v192, v193
	v_cvt_pk_bf16_f32 v193, v184, v185
	v_lshl_add_u64 v[184:185], s[12:13], 0, v[194:195]
	v_pk_mul_f32 v[196:197], v[196:197], s[18:19] op_sel_hi:[1,0]
	v_lshl_add_u64 v[184:185], v[184:185], 0, s[48:49]
	v_pk_mul_f32 v[196:197], v[96:97], v[196:197]
	v_lshl_add_u64 v[184:185], v[184:185], 0, s[4:5]
	v_cvt_pk_bf16_f32 v192, v196, v197
	v_lshl_add_u64 v[194:195], v[184:185], 0, v[136:137]
	global_store_dwordx4 v[194:195], v[190:193], off
	v_cvt_f32_ubyte1_e32 v185, v182
	v_cvt_f32_ubyte0_e32 v184, v182
	v_cvt_f32_ubyte3_e32 v191, v182
	v_cvt_f32_ubyte2_e32 v190, v182
	v_cvt_f32_ubyte1_e32 v193, v183
	v_cvt_f32_ubyte0_e32 v192, v183
	v_cvt_f32_ubyte3_e32 v197, v183
	v_cvt_f32_ubyte2_e32 v196, v183
	v_pk_mul_f32 v[184:185], v[184:185], s[18:19] op_sel_hi:[1,0]
	v_pk_mul_f32 v[190:191], v[190:191], s[18:19] op_sel_hi:[1,0]
	v_pk_mul_f32 v[192:193], v[192:193], s[18:19] op_sel_hi:[1,0]
	v_pk_mul_f32 v[182:183], v[196:197], s[18:19] op_sel_hi:[1,0]
	v_pk_mul_f32 v[184:185], v[68:69], v[184:185]
	v_pk_mul_f32 v[190:191], v[70:71], v[190:191]
	v_pk_mul_f32 v[192:193], v[64:65], v[192:193]
	v_pk_mul_f32 v[196:197], v[66:67], v[182:183]
; __device__ __forceinline__ u32x4 pack8_bf16(const float (&o)[8]) { u32x4 w; w.x = cvt_pk_bf16(o[0], o[1]); w.y = cvt_pk_bf16(o[2], o[3]); w.z = cvt_pk_bf16(o[4], o[5]); w.w = cvt_pk_bf16(o[6], o[7]); return w; }
;     __device__ __forceinline__ void operator()(f32x4 (&acc)[2][2][4][2], const Unit& u, int wr, int wc, int fr, int fq) const {
;     ...
;                 for (int bj = 0; bj < 2; ++bj) {
;                     const size_t off = (size_t)(row0 + ai * HALF + m * 16) * 1024 + u.pn * BM + bj * HALF + wc * 32 + 8 * fq;
;                     const u32x2 b = gbv[ai][m][bj]; float o[8];
; #pragma unroll
;                     for (int k = 0; k < 8; ++k) { const float qb = (float)((b[k >> 2] >> (8 * (k & 3))) & 255u); o[k] = acc[ai][bj][m][k >> 2][k & 3] * (qb * (1.0f / 255.0f)); }
;                     *(u32x4*)(MIXED + off) = pack8_bf16(o);
	v_cvt_pk_bf16_f32 v182, v184, v185
	v_cvt_pk_bf16_f32 v183, v190, v191
	v_cvt_pk_bf16_f32 v184, v192, v193
	v_cvt_pk_bf16_f32 v185, v196, v197
	global_store_dwordx4 v[194:195], v[182:185], off offset:256
	v_cvt_f32_ubyte1_e32 v191, v181
	v_cvt_f32_ubyte0_e32 v190, v181
	v_cvt_f32_ubyte1_e32 v183, v180
	v_cvt_f32_ubyte0_e32 v182, v180
	v_cvt_f32_ubyte3_e32 v185, v180
	v_cvt_f32_ubyte2_e32 v184, v180
	v_cvt_f32_ubyte3_e32 v193, v181
	v_cvt_f32_ubyte2_e32 v192, v181
	v_pk_mul_f32 v[182:183], v[182:183], s[18:19] op_sel_hi:[1,0]
	v_pk_mul_f32 v[184:185], v[184:185], s[18:19] op_sel_hi:[1,0]
	v_pk_mul_f32 v[190:191], v[190:191], s[18:19] op_sel_hi:[1,0]
	v_pk_mul_f32 v[180:181], v[192:193], s[18:19] op_sel_hi:[1,0]
	v_pk_mul_f32 v[182:183], v[60:61], v[182:183]
	v_pk_mul_f32 v[184:185], v[62:63], v[184:185]
	v_pk_mul_f32 v[190:191], v[56:57], v[190:191]
	v_pk_mul_f32 v[192:193], v[58:59], v[180:181]
	v_cvt_pk_bf16_f32 v180, v182, v183
	v_cvt_pk_bf16_f32 v181, v184, v185
	v_cvt_pk_bf16_f32 v182, v190, v191
	v_cvt_pk_bf16_f32 v183, v192, v193
	v_lshl_add_u64 v[184:185], v[176:177], 0, v[136:137]
	global_store_dwordx4 v[184:185], v[180:183], off
	v_cvt_f32_ubyte1_e32 v177, v178
	v_cvt_f32_ubyte0_e32 v176, v178
	v_cvt_f32_ubyte3_e32 v181, v178
	v_cvt_f32_ubyte2_e32 v180, v178
	v_cvt_f32_ubyte1_e32 v183, v179
	v_cvt_f32_ubyte0_e32 v182, v179
	v_cvt_f32_ubyte3_e32 v191, v179
	v_cvt_f32_ubyte2_e32 v190, v179
	v_pk_mul_f32 v[176:177], v[176:177], s[18:19] op_sel_hi:[1,0]
	v_pk_mul_f32 v[180:181], v[180:181], s[18:19] op_sel_hi:[1,0]
	v_pk_mul_f32 v[182:183], v[182:183], s[18:19] op_sel_hi:[1,0]
	v_pk_mul_f32 v[178:179], v[190:191], s[18:19] op_sel_hi:[1,0]
	v_pk_mul_f32 v[176:177], v[28:29], v[176:177]
	v_pk_mul_f32 v[180:181], v[30:31], v[180:181]
	v_pk_mul_f32 v[182:183], v[24:25], v[182:183]
	v_pk_mul_f32 v[190:191], v[26:27], v[178:179]
	v_cvt_pk_bf16_f32 v176, v176, v177
	v_cvt_pk_bf16_f32 v177, v180, v181
	v_cvt_pk_bf16_f32 v178, v182, v183
	v_cvt_pk_bf16_f32 v179, v190, v191
	global_store_dwordx4 v[184:185], v[176:179], off offset:256
	v_cvt_f32_ubyte1_e32 v181, v175
	v_cvt_f32_ubyte0_e32 v180, v175
	v_cvt_f32_ubyte1_e32 v177, v174
	v_cvt_f32_ubyte0_e32 v176, v174
	v_cvt_f32_ubyte3_e32 v179, v174
	v_cvt_f32_ubyte2_e32 v178, v174
	v_cvt_f32_ubyte3_e32 v183, v175
	v_cvt_f32_ubyte2_e32 v182, v175
	v_pk_mul_f32 v[176:177], v[176:177], s[18:19] op_sel_hi:[1,0]
	v_pk_mul_f32 v[178:179], v[178:179], s[18:19] op_sel_hi:[1,0]
	v_pk_mul_f32 v[180:181], v[180:181], s[18:19] op_sel_hi:[1,0]
	v_pk_mul_f32 v[174:175], v[182:183], s[18:19] op_sel_hi:[1,0]
	v_pk_mul_f32 v[176:177], v[52:53], v[176:177]
	v_pk_mul_f32 v[178:179], v[54:55], v[178:179]
	v_pk_mul_f32 v[180:181], v[48:49], v[180:181]
	v_pk_mul_f32 v[182:183], v[50:51], v[174:175]
	v_cvt_pk_bf16_f32 v174, v176, v177
	v_cvt_pk_bf16_f32 v175, v178, v179
	v_cvt_pk_bf16_f32 v176, v180, v181
	v_cvt_pk_bf16_f32 v177, v182, v183
	v_lshl_add_u64 v[178:179], v[170:171], 0, v[136:137]
	global_store_dwordx4 v[178:179], v[174:177], off
	v_cvt_f32_ubyte1_e32 v171, v172
	v_cvt_f32_ubyte0_e32 v170, v172
	v_cvt_f32_ubyte3_e32 v175, v172
	v_cvt_f32_ubyte2_e32 v174, v172
	v_cvt_f32_ubyte1_e32 v177, v173
	v_cvt_f32_ubyte0_e32 v176, v173
	v_cvt_f32_ubyte3_e32 v181, v173
	v_cvt_f32_ubyte2_e32 v180, v173
	v_pk_mul_f32 v[170:171], v[170:171], s[18:19] op_sel_hi:[1,0]
	v_pk_mul_f32 v[174:175], v[174:175], s[18:19] op_sel_hi:[1,0]
	v_pk_mul_f32 v[176:177], v[176:177], s[18:19] op_sel_hi:[1,0]
	v_pk_mul_f32 v[172:173], v[180:181], s[18:19] op_sel_hi:[1,0]
	v_pk_mul_f32 v[170:171], v[20:21], v[170:171]
	v_pk_mul_f32 v[174:175], v[22:23], v[174:175]
	v_pk_mul_f32 v[176:177], v[16:17], v[176:177]
	v_pk_mul_f32 v[180:181], v[18:19], v[172:173]
	v_cvt_pk_bf16_f32 v170, v170, v171
	v_cvt_pk_bf16_f32 v171, v174, v175
	v_cvt_pk_bf16_f32 v172, v176, v177
; __device__ __forceinline__ u32x4 pack8_bf16(const float (&o)[8]) { u32x4 w; w.x = cvt_pk_bf16(o[0], o[1]); w.y = cvt_pk_bf16(o[2], o[3]); w.z = cvt_pk_bf16(o[4], o[5]); w.w = cvt_pk_bf16(o[6], o[7]); return w; }
;     __device__ __forceinline__ void operator()(f32x4 (&acc)[2][2][4][2], const Unit& u, int wr, int wc, int fr, int fq) const {
;     ...
;                 for (int bj = 0; bj < 2; ++bj) {
;                     const size_t off = (size_t)(row0 + ai * HALF + m * 16) * 1024 + u.pn * BM + bj * HALF + wc * 32 + 8 * fq;
;                     const u32x2 b = gbv[ai][m][bj]; float o[8];
; #pragma unroll
;                     for (int k = 0; k < 8; ++k) { const float qb = (float)((b[k >> 2] >> (8 * (k & 3))) & 255u); o[k] = acc[ai][bj][m][k >> 2][k & 3] * (qb * (1.0f / 255.0f)); }
;                     *(u32x4*)(MIXED + off) = pack8_bf16(o);
	v_cvt_pk_bf16_f32 v173, v180, v181
	global_store_dwordx4 v[178:179], v[170:173], off offset:256
	v_cvt_f32_ubyte1_e32 v175, v169
	v_cvt_f32_ubyte0_e32 v174, v169
	v_cvt_f32_ubyte1_e32 v171, v168
	v_cvt_f32_ubyte0_e32 v170, v168
	v_cvt_f32_ubyte3_e32 v173, v168
	v_cvt_f32_ubyte2_e32 v172, v168
	v_cvt_f32_ubyte3_e32 v177, v169
	v_cvt_f32_ubyte2_e32 v176, v169
	v_pk_mul_f32 v[170:171], v[170:171], s[18:19] op_sel_hi:[1,0]
	v_pk_mul_f32 v[172:173], v[172:173], s[18:19] op_sel_hi:[1,0]
	v_pk_mul_f32 v[174:175], v[174:175], s[18:19] op_sel_hi:[1,0]
	v_pk_mul_f32 v[168:169], v[176:177], s[18:19] op_sel_hi:[1,0]
	v_pk_mul_f32 v[170:171], v[44:45], v[170:171]
	v_pk_mul_f32 v[172:173], v[46:47], v[172:173]
	v_pk_mul_f32 v[174:175], v[40:41], v[174:175]
	v_pk_mul_f32 v[176:177], v[42:43], v[168:169]
	v_cvt_pk_bf16_f32 v168, v170, v171
	v_cvt_pk_bf16_f32 v169, v172, v173
	v_cvt_pk_bf16_f32 v170, v174, v175
	v_cvt_pk_bf16_f32 v171, v176, v177
	v_lshl_add_u64 v[172:173], v[164:165], 0, v[136:137]
	global_store_dwordx4 v[172:173], v[168:171], off
	v_cvt_f32_ubyte1_e32 v165, v166
	v_cvt_f32_ubyte0_e32 v164, v166
	v_cvt_f32_ubyte3_e32 v169, v166
	v_cvt_f32_ubyte2_e32 v168, v166
	v_cvt_f32_ubyte1_e32 v171, v167
	v_cvt_f32_ubyte0_e32 v170, v167
	v_cvt_f32_ubyte3_e32 v175, v167
	v_cvt_f32_ubyte2_e32 v174, v167
	v_pk_mul_f32 v[164:165], v[164:165], s[18:19] op_sel_hi:[1,0]
	v_pk_mul_f32 v[168:169], v[168:169], s[18:19] op_sel_hi:[1,0]
	v_pk_mul_f32 v[170:171], v[170:171], s[18:19] op_sel_hi:[1,0]
	v_pk_mul_f32 v[166:167], v[174:175], s[18:19] op_sel_hi:[1,0]
	v_pk_mul_f32 v[164:165], v[12:13], v[164:165]
	v_pk_mul_f32 v[168:169], v[14:15], v[168:169]
	v_pk_mul_f32 v[170:171], v[8:9], v[170:171]
	v_pk_mul_f32 v[174:175], v[10:11], v[166:167]
	v_cvt_pk_bf16_f32 v164, v164, v165
	v_cvt_pk_bf16_f32 v165, v168, v169
	v_cvt_pk_bf16_f32 v166, v170, v171
	v_cvt_pk_bf16_f32 v167, v174, v175
	global_store_dwordx4 v[172:173], v[164:167], off offset:256
	v_cvt_f32_ubyte1_e32 v169, v163
	v_cvt_f32_ubyte0_e32 v168, v163
	v_cvt_f32_ubyte1_e32 v165, v162
	v_cvt_f32_ubyte0_e32 v164, v162
	v_cvt_f32_ubyte3_e32 v167, v162
	v_cvt_f32_ubyte2_e32 v166, v162
	v_cvt_f32_ubyte3_e32 v171, v163
	v_cvt_f32_ubyte2_e32 v170, v163
	v_pk_mul_f32 v[164:165], v[164:165], s[18:19] op_sel_hi:[1,0]
	v_pk_mul_f32 v[166:167], v[166:167], s[18:19] op_sel_hi:[1,0]
	v_pk_mul_f32 v[168:169], v[168:169], s[18:19] op_sel_hi:[1,0]
	v_pk_mul_f32 v[162:163], v[170:171], s[18:19] op_sel_hi:[1,0]
	v_pk_mul_f32 v[164:165], v[36:37], v[164:165]
	v_pk_mul_f32 v[166:167], v[38:39], v[166:167]
	v_pk_mul_f32 v[168:169], v[32:33], v[168:169]
	v_pk_mul_f32 v[170:171], v[34:35], v[162:163]
	v_cvt_pk_bf16_f32 v162, v164, v165
	v_cvt_pk_bf16_f32 v163, v166, v167
	v_cvt_pk_bf16_f32 v164, v168, v169
	v_cvt_pk_bf16_f32 v165, v170, v171
	v_lshl_add_u64 v[166:167], v[158:159], 0, v[136:137]
	global_store_dwordx4 v[166:167], v[162:165], off
	v_cvt_f32_ubyte1_e32 v159, v160
	v_cvt_f32_ubyte0_e32 v158, v160
	v_cvt_f32_ubyte3_e32 v163, v160
	v_cvt_f32_ubyte2_e32 v162, v160
	v_cvt_f32_ubyte1_e32 v165, v161
	v_cvt_f32_ubyte0_e32 v164, v161
	v_cvt_f32_ubyte3_e32 v169, v161
	v_cvt_f32_ubyte2_e32 v168, v161
	v_pk_mul_f32 v[158:159], v[158:159], s[18:19] op_sel_hi:[1,0]
	v_pk_mul_f32 v[162:163], v[162:163], s[18:19] op_sel_hi:[1,0]
	v_pk_mul_f32 v[164:165], v[164:165], s[18:19] op_sel_hi:[1,0]
	v_pk_mul_f32 v[160:161], v[168:169], s[18:19] op_sel_hi:[1,0]
	v_pk_mul_f32 v[158:159], v[4:5], v[158:159]
	v_pk_mul_f32 v[162:163], v[6:7], v[162:163]
	v_pk_mul_f32 v[164:165], v[0:1], v[164:165]
	v_pk_mul_f32 v[168:169], v[2:3], v[160:161]
	v_cvt_pk_bf16_f32 v158, v158, v159
	v_cvt_pk_bf16_f32 v159, v162, v163
	v_cvt_pk_bf16_f32 v160, v164, v165
	v_cvt_pk_bf16_f32 v161, v168, v169
	global_store_dwordx4 v[166:167], v[158:161], off offset:256
	s_cbranch_execnz .LBB0_801

;     __device__ __forceinline__ void operator()(f32x4 (&acc)[2][2][4][2], const Unit& u, int wr, int wc, int fr, int fq) const {
;         if (u.kh == 0) { half0(acc, u, wr, wc, fr, fq); return; }
;         const int row0 = u.pm * BM + wr * 64 + fr;
;         u32x2 gbv[2][4][2];
; #pragma unroll
;         for (int ai = 0; ai < 2; ++ai)
; #pragma unroll
;             for (int m = 0; m < 4; ++m)
; #pragma unroll
;                 for (int bj = 0; bj < 2; ++bj) gbv[ai][m][bj] = *(const u32x2*)(GB + (size_t)(row0 + ai * HALF + m * 16) * 1024 + u.pn * BM + bj * HALF + wc * 32 + 8 * fq);
.LBB0_806:
	s_lshl_b32 s92, s77, 8
	s_ashr_i32 s93, s92, 31
	v_lshl_add_u64 v[250:251], v[140:141], 0, s[92:93]
	v_lshlrev_b64 v[252:253], 10, v[150:151]
	v_lshl_add_u64 v[250:251], v[250:251], 0, v[252:253]
	global_load_dwordx2 v[218:219], v[250:251], off
	global_load_dwordx2 v[220:221], v[250:251], off offset:128
	s_mov_b64 s[92:93], 0x4000
	v_lshl_add_u64 v[252:253], v[250:251], 0, s[92:93]
	global_load_dwordx2 v[222:223], v[252:253], off
	global_load_dwordx2 v[224:225], v[252:253], off offset:128
	s_mov_b64 s[92:93], 0x8000
	v_lshl_add_u64 v[252:253], v[250:251], 0, s[92:93]
	global_load_dwordx2 v[226:227], v[252:253], off
	global_load_dwordx2 v[228:229], v[252:253], off offset:128
	s_mov_b64 s[92:93], 0xc000
	v_lshl_add_u64 v[252:253], v[250:251], 0, s[92:93]
	global_load_dwordx2 v[230:231], v[252:253], off
	global_load_dwordx2 v[232:233], v[252:253], off offset:128
	s_mov_b64 s[92:93], 0x20000
	v_lshl_add_u64 v[252:253], v[250:251], 0, s[92:93]
	global_load_dwordx2 v[234:235], v[252:253], off
	global_load_dwordx2 v[236:237], v[252:253], off offset:128
	s_mov_b64 s[92:93], 0x24000
	v_lshl_add_u64 v[252:253], v[250:251], 0, s[92:93]
	global_load_dwordx2 v[238:239], v[252:253], off
	global_load_dwordx2 v[240:241], v[252:253], off offset:128
	s_mov_b64 s[92:93], 0x28000
	v_lshl_add_u64 v[252:253], v[250:251], 0, s[92:93]
	global_load_dwordx2 v[242:243], v[252:253], off
	global_load_dwordx2 v[244:245], v[252:253], off offset:128
	s_mov_b64 s[92:93], 0x2c000
	v_lshl_add_u64 v[252:253], v[250:251], 0, s[92:93]
	global_load_dwordx2 v[246:247], v[252:253], off
	global_load_dwordx2 v[248:249], v[252:253], off offset:128
	s_branch .LBB0_800
